# attnA: LDS-DMA pieces issued in saddr form with wave-uniform LDS targets held in SGPRs (18 fewer VALU per tile)
# speedup vs baseline: 1.0201x; 1.0138x over previous
.LBB0_177:
	v_and_b32_e32 v0, 63, v154
	v_readlane_b32 s4, v245, 5
	v_lshlrev_b32_e32 v0, 2, v0
	v_readlane_b32 s14, v245, 15
	v_readlane_b32 s15, v245, 16
	s_nop 4
	global_load_dword v1, v0, s[14:15]
	global_load_dword v2, v0, s[14:15] offset:256
	global_load_dword v3, v0, s[14:15] offset:512
	global_load_dword v4, v0, s[14:15] offset:768
	v_mbcnt_lo_u32_b32 v0, -1, 0
	v_mbcnt_hi_u32_b32 v12, -1, v0
	v_and_b32_e32 v17, 64, v12
	v_xor_b32_e32 v18, 32, v12
	v_add_u32_e32 v17, 64, v17
	v_lshrrev_b32_e32 v5, 6, v154
	v_bfe_u32 v10, v154, 4, 2
	v_bfe_u32 v11, v154, 3, 3
	v_cmp_lt_i32_e32 vcc, v18, v17
	v_or_b32_e32 v13, 0x7fffffe0, v10
	v_lshl_or_b32 v16, v5, 3, v11
	v_cndmask_b32_e32 v18, v12, v18, vcc
	s_movk_i32 s20, 0x1800
	v_lshl_add_u32 v24, v5, 2, v13
	v_lshrrev_b32_e32 v25, 1, v16
	v_lshlrev_b32_e32 v158, 2, v18
	v_mul_lo_u32 v157, v24, s20
	v_xor_b32_e32 v24, v25, v154
	v_xor_b32_e32 v19, 16, v12
	v_cmp_lt_i32_e32 vcc, v19, v17
	v_xor_b32_e32 v20, 8, v12
	v_xor_b32_e32 v21, 4, v12
	v_cndmask_b32_e32 v19, v12, v19, vcc
	v_lshlrev_b32_e32 v19, 2, v19
	v_cmp_lt_i32_e32 vcc, v20, v17
	v_xor_b32_e32 v22, 2, v12
	v_xor_b32_e32 v23, 1, v12
	v_cndmask_b32_e32 v20, v12, v20, vcc
	v_cmp_lt_i32_e32 vcc, v21, v17
	v_readlane_b32 s8, v245, 9
	s_mov_b32 s8, 0x3fb8aa3b
	v_readlane_b32 s12, v245, 13
	s_mov_b32 s12, 0xc2ce8ed0
	v_readlane_b32 s13, v245, 14
	s_mov_b32 s13, 0x42b17218
	v_mov_b32_e32 v8, 0x7f800000
	v_add_u32_e32 v15, 4, v5
	v_readlane_b32 s10, v245, 11
	v_readlane_b32 s11, v245, 12
	s_not_b32 s4, s2
	s_ashr_i32 s3, s2, 31
	v_lshlrev_b32_e32 v14, 2, v10
	v_and_b32_e32 v6, 31, v154
	v_bfe_u32 v7, v154, 5, 1
	s_add_i32 s21, s33, s4
	s_lshl_b64 s[10:11], s[2:3], 16
	v_bitop3_b32 v14, v14, v154, 12 bitop3:0x78
	v_bfe_u32 v9, v154, 2, 2
	v_mul_u32_u24_e32 v16, 0xc00, v16
	v_lshl_add_u32 v13, v15, 2, v13
	v_and_or_b32 v14, v154, 3, v14
	v_lshl_or_b32 v172, v5, 5, v6
	s_add_u32 s10, s38, s10
	s_movk_i32 s3, 0x6000
	v_readlane_b32 s5, v245, 6
	v_readlane_b32 s6, v245, 7
	v_mov_b32_e32 v113, 0
	v_lshlrev_b32_e32 v156, 10, v5
	v_lshlrev_b32_e32 v14, 4, v14
	v_mul_lo_u32 v166, v13, s20
	v_lshlrev_b32_e32 v168, 6, v9
	s_addc_u32 s11, s39, s11
	v_lshlrev_b32_e32 v112, 8, v154
	v_readlane_b32 s7, v245, 8
	v_readlane_b32 s9, v245, 10
	v_readlane_b32 s16, v245, 17
	v_readlane_b32 s17, v245, 18
	s_movk_i32 s5, 0x200
	s_movk_i32 s6, 0x100
	v_lshlrev_b32_e32 v0, 3, v7
	v_lshl_add_u64 v[114:115], s[10:11], 0, v[112:113]
	v_lshlrev_b32_e32 v112, 4, v7
	s_mov_b32 s9, 0
	v_lshrrev_b32_e32 v155, 7, v154
	v_cmp_gt_u32_e64 s[4:5], s5, v154
	v_cmp_gt_u32_e64 s[6:7], s6, v154
	v_add_u32_e32 v159, 0x30000, v157
	s_waitcnt vmcnt(2)
	v_mul_f32_e32 v18, v1, v2
	ds_bpermute_b32 v18, v158, v18
	s_waitcnt vmcnt(0)
	v_mul_f32_e32 v25, v3, v4
	ds_bpermute_b32 v25, v158, v25
	v_add_u32_e32 v160, 0x48000, v157
	v_add_u32_e32 v161, 0x60000, v157
	s_waitcnt lgkmcnt(1)
	v_fmac_f32_e32 v18, v1, v2
	ds_bpermute_b32 v1, v19, v18
	s_waitcnt lgkmcnt(1)
	v_fmac_f32_e32 v25, v3, v4
	ds_bpermute_b32 v2, v19, v25
	v_lshlrev_b32_e32 v4, 2, v20
	v_cndmask_b32_e32 v3, v12, v21, vcc
	s_waitcnt lgkmcnt(1)
	v_add_f32_e32 v1, v18, v1
	ds_bpermute_b32 v18, v4, v1
	s_waitcnt lgkmcnt(1)
	v_add_f32_e32 v2, v25, v2
	ds_bpermute_b32 v4, v4, v2
	v_lshlrev_b32_e32 v3, 2, v3
	v_cmp_lt_i32_e32 vcc, v22, v17
	s_waitcnt lgkmcnt(1)
	v_add_f32_e32 v1, v1, v18
	v_add_u32_e32 v162, 0x78000, v157
	s_waitcnt lgkmcnt(0)
	v_add_f32_e32 v2, v2, v4
	ds_bpermute_b32 v4, v3, v1
	ds_bpermute_b32 v3, v3, v2
	v_cndmask_b32_e32 v19, v12, v22, vcc
	v_cmp_lt_i32_e32 vcc, v23, v17
	v_lshlrev_b32_e32 v17, 2, v19
	s_waitcnt lgkmcnt(1)
	v_add_f32_e32 v1, v1, v4
	s_waitcnt lgkmcnt(0)
	v_add_f32_e32 v2, v2, v3
	ds_bpermute_b32 v3, v17, v1
	ds_bpermute_b32 v4, v17, v2
	v_cndmask_b32_e32 v12, v12, v23, vcc
	v_lshlrev_b32_e32 v12, 2, v12
	v_or_b32_e32 v163, 0x1000, v14
	s_waitcnt lgkmcnt(1)
	v_add_f32_e32 v1, v1, v3
	s_waitcnt lgkmcnt(0)
	v_add_f32_e32 v2, v2, v4
	ds_bpermute_b32 v3, v12, v1
	ds_bpermute_b32 v4, v12, v2
	v_lshlrev_b32_e32 v12, 3, v24
	v_and_or_b32 v164, v12, 56, v16
	v_xor_b32_e32 v169, 64, v168
	s_waitcnt lgkmcnt(1)
	v_add_f32_e32 v1, v1, v3
	s_waitcnt lgkmcnt(0)
	v_add_f32_e32 v2, v2, v4
	v_mul_f32_e32 v3, 0x3fb8aa3b, v1
	v_mul_f32_e32 v4, 0x3fb8aa3b, v2
	v_fma_f32 v17, v1, s8, -v3
	v_rndne_f32_e32 v18, v3
	v_fma_f32 v19, v2, s8, -v4
	v_rndne_f32_e32 v20, v4
	v_fmac_f32_e32 v17, 0x32a5705f, v1
	v_sub_f32_e32 v3, v3, v18
	v_fmac_f32_e32 v19, 0x32a5705f, v2
	v_sub_f32_e32 v4, v4, v20
	v_add_f32_e32 v3, v3, v17
	v_cvt_i32_f32_e32 v18, v18
	v_add_f32_e32 v4, v4, v19
	v_exp_f32_e32 v3, v3
	v_cvt_i32_f32_e32 v20, v20
	v_exp_f32_e32 v4, v4
	v_cmp_ngt_f32_e32 vcc, s12, v1
	v_ldexp_f32 v3, v3, v18
	v_xor_b32_e32 v170, 0x80, v168
	v_ldexp_f32 v4, v4, v20
	v_cndmask_b32_e32 v3, 0, v3, vcc
	v_cmp_ngt_f32_e32 vcc, s12, v2
	v_xor_b32_e32 v171, 0xc0, v168
	v_lshl_add_u64 v[116:117], s[16:17], 0, v[112:113]
	v_cndmask_b32_e32 v4, 0, v4, vcc
	v_cmp_nlt_f32_e32 vcc, s13, v1
	v_lshlrev_b32_e32 v118, 1, v0
	v_add_u32_e32 v178, 0x1000, v156
	v_cndmask_b32_e32 v1, v8, v3, vcc
	v_cmp_nlt_f32_e32 vcc, s13, v2
	v_lshrrev_b32_e32 v3, 1, v154
	v_bitop3_b32 v3, v7, v3, 7 bitop3:0x78
	v_cndmask_b32_e32 v2, v8, v4, vcc
	v_sub_f32_e32 v1, v1, v2
	v_add_f32_e32 v165, 0x3e4ccccd, v1
	v_lshl_or_b32 v1, v15, 3, v11
	v_lshrrev_b32_e32 v2, 1, v1
	v_xor_b32_e32 v2, v2, v154
	v_mul_u32_u24_e32 v1, 0xc00, v1
	v_lshlrev_b32_e32 v2, 3, v2
	v_and_or_b32 v167, v2, 56, v1
	v_lshlrev_b32_e32 v1, 7, v6
	v_bfe_u32 v4, v154, 1, 3
	v_lshlrev_b32_e32 v2, 2, v7
	v_mul_u32_u24_e32 v6, 0x1800, v10
	v_lshlrev_b32_e32 v8, 1, v154
	v_lshlrev_b32_e32 v11, 3, v154
	v_bitop3_b32 v12, v7, v4, 2 bitop3:0x36
	v_bitop3_b32 v13, v7, v4, 4 bitop3:0x36
	v_bitop3_b32 v4, v7, v4, 6 bitop3:0x36
	v_or_b32_e32 v9, v2, v9
	v_mad_u32_u24 v5, v5, s3, v6
	v_and_b32_e32 v8, 32, v8
	v_and_b32_e32 v11, 24, v11
	v_lshlrev_b32_e32 v3, 4, v3
	v_lshlrev_b32_e32 v12, 4, v12
	v_lshlrev_b32_e32 v13, 4, v13
	v_lshlrev_b32_e32 v4, 4, v4
	v_lshlrev_b32_e32 v9, 8, v9
	v_or_b32_e32 v5, v5, v14
	v_or3_b32 v173, v8, v11, v9
	v_add_u32_e32 v174, 0x1000, v5
	v_add_u32_e32 v175, 0x19000, v5
	v_add_u32_e32 v176, 0x31000, v5
	v_add_u32_e32 v177, 0x49000, v5
	v_add_u32_e32 v179, 0x2000, v156
	v_add_u32_e32 v180, 0x3000, v156
	v_or_b32_e32 v181, 0x4000, v156
	v_add_u32_e32 v182, 0x5000, v156
	s_mov_b64 s[10:11], 0x60000
	v_add_u32_e32 v183, 0x6000, v156
	v_add_u32_e32 v184, 0x7000, v156
	v_or_b32_e32 v185, 0x8000, v156
	v_add_u32_e32 v186, 0x9000, v156
	v_add_u32_e32 v187, 0xa000, v156
	v_add_u32_e32 v188, 0xb000, v156
	v_add_u32_e32 v189, v1, v3
	v_add_u32_e32 v190, v1, v12
	v_add_u32_e32 v191, v1, v13
	v_add_u32_e32 v192, v1, v4
	s_mov_b32 s3, 0x3e38aa3b
	s_mov_b64 s[12:13], 0xc0000
	v_lshlrev_b32_e32 v120, 1, v2
	v_mov_b32_e32 v193, 0x3727c5ac
	s_mov_b32 s22, 0x800000
	s_mov_b32 s8, 0
	s_mov_b32 s23, 0
	v_readlane_b32 s18, v245, 19
	v_readlane_b32 s19, v245, 20
	s_nop 0
	v_readfirstlane_b32 s72, v183
	v_readfirstlane_b32 s73, v184
	v_readfirstlane_b32 s74, v185
	v_readfirstlane_b32 s75, v186
	v_readfirstlane_b32 s76, v187
	v_readfirstlane_b32 s77, v188
	v_readfirstlane_b32 s78, v156
	v_readfirstlane_b32 s79, v178
	v_readfirstlane_b32 s80, v179
	v_readfirstlane_b32 s81, v180
	v_readfirstlane_b32 s82, v181
	v_readfirstlane_b32 s83, v182
	s_branch .LBB0_180

.LBB0_184:
	s_add_i32 s18, s8, 1
	s_cmp_ge_u32 s18, s27
	s_cbranch_scc1 .LBB0_186
	s_add_u32 s68, s14, s10
	s_addc_u32 s69, s15, s11
	s_mov_b32 m0, s72
	s_nop 0
	global_load_lds_dwordx4 v112, s[68:69]
	s_mov_b32 m0, s73
	s_nop 0
	global_load_lds_dwordx4 v140, s[68:69]
	s_mov_b32 m0, s74
	s_nop 0
	global_load_lds_dwordx4 v122, s[68:69]
	s_mov_b32 m0, s75
	s_nop 0
	global_load_lds_dwordx4 v124, s[68:69]
	s_mov_b32 m0, s76
	s_nop 0
	global_load_lds_dwordx4 v126, s[68:69]
	s_mov_b32 m0, s77
	s_nop 0
	global_load_lds_dwordx4 v128, s[68:69]

.LBB0_190:
	s_or_b64 exec, exec, s[18:19]
	s_waitcnt vmcnt(0)
	s_cmp_ge_u32 s8, s26
	s_waitcnt vmcnt(0) lgkmcnt(0)
	s_barrier
	s_cbranch_scc1 .LBB0_192
	s_add_u32 s68, s14, s12
	s_addc_u32 s69, s15, s13
	s_mov_b32 m0, s78
	s_nop 0
	global_load_lds_dwordx4 v112, s[68:69]
	s_mov_b32 m0, s79
	s_nop 0
	global_load_lds_dwordx4 v140, s[68:69]
	s_mov_b32 m0, s80
	s_nop 0
	global_load_lds_dwordx4 v122, s[68:69]
	s_mov_b32 m0, s81
	s_nop 0
	global_load_lds_dwordx4 v124, s[68:69]
	s_mov_b32 m0, s82
	s_nop 0
	global_load_lds_dwordx4 v126, s[68:69]
	s_mov_b32 m0, s83
	s_nop 0
	global_load_lds_dwordx4 v128, s[68:69]

.LBB0_198:
	s_add_i32 s14, s8, 1
	s_cmp_ge_u32 s14, s27
	s_cbranch_scc1 .LBB0_200
	s_add_u32 s68, s16, s10
	s_addc_u32 s69, s17, s11
	s_mov_b32 m0, s72
	s_nop 0
	global_load_lds_dwordx4 v112, s[68:69]
	s_mov_b32 m0, s73
	s_nop 0
	global_load_lds_dwordx4 v130, s[68:69]
	s_mov_b32 m0, s74
	s_nop 0
	global_load_lds_dwordx4 v122, s[68:69]
	s_mov_b32 m0, s75
	s_nop 0
	global_load_lds_dwordx4 v124, s[68:69]
	s_mov_b32 m0, s76
	s_nop 0
	global_load_lds_dwordx4 v126, s[68:69]
	s_mov_b32 m0, s77
	s_nop 0
	global_load_lds_dwordx4 v128, s[68:69]

.LBB0_204:
	s_or_b64 exec, exec, s[14:15]
	s_waitcnt vmcnt(0)
	s_cmp_ge_u32 s8, s26
	s_waitcnt vmcnt(0) lgkmcnt(0)
	s_barrier
	s_cbranch_scc1 .LBB0_206
	s_add_u32 s68, s16, s12
	s_addc_u32 s69, s17, s13
	s_mov_b32 m0, s78
	s_nop 0
	global_load_lds_dwordx4 v112, s[68:69]
	s_mov_b32 m0, s79
	s_nop 0
	global_load_lds_dwordx4 v130, s[68:69]
	s_mov_b32 m0, s80
	s_nop 0
	global_load_lds_dwordx4 v122, s[68:69]
	s_mov_b32 m0, s81
	s_nop 0
	global_load_lds_dwordx4 v124, s[68:69]
	s_mov_b32 m0, s82
	s_nop 0
	global_load_lds_dwordx4 v126, s[68:69]
	s_mov_b32 m0, s83
	s_nop 0
	global_load_lds_dwordx4 v128, s[68:69]
